# residual-tile prefetch via LDS-DMA dump inside w2 and w_out K-loops
# baseline (speedup 1.0000x reference)
.LBB0_44:
	s_add_u32 s50, s28, 0x100
	s_addc_u32 s51, s29, 0
	s_add_i32 s38, 0, 0x10000
	v_add_u32_e32 v78, s38, v163
	ds_read_b128 v[66:69], v78
	ds_read_b128 v[70:73], v78 offset:1024
	ds_read_b128 v[74:77], v78 offset:2048
	ds_read_b128 v[78:81], v78 offset:3072
	s_cmpk_eq_i32 s75, 0x7c
	s_cselect_b32 s55, s27, s51
	s_cselect_b32 s54, s71, s50
	s_cselect_b32 s53, s25, s74
	s_cselect_b32 s52, s72, s73
	v_lshl_add_u64 v[156:157], s[28:29], 0, v[150:151]
	s_add_i32 m0, s9, 0xc000
	ds_read_b128 v[152:155], v165
	ds_read_b128 v[166:169], v165 offset:1024
	ds_read_b128 v[170:173], v165 offset:2048
	ds_read_b128 v[174:177], v165 offset:3072
	ds_read_b128 v[178:181], v165 offset:4096
	ds_read_b128 v[182:185], v165 offset:5120
	ds_read_b128 v[186:189], v165 offset:6144
	ds_read_b128 v[190:193], v165 offset:7168
	global_load_lds_dwordx4 v[156:157], off
	v_lshl_add_u64 v[156:157], s[28:29], 0, v[148:149]
	s_add_i32 m0, s9, 0xe000
	s_nop 0
	global_load_lds_dwordx4 v[156:157], off
	s_waitcnt lgkmcnt(8)
	s_barrier
	s_waitcnt lgkmcnt(0)
	s_setprio 1
	s_waitcnt lgkmcnt(0)
	v_mfma_f32_16x16x32_bf16 v[142:145], v[66:69], v[152:155], v[142:145]
	v_mfma_f32_16x16x32_bf16 v[138:141], v[74:77], v[152:155], v[138:141]
	v_mfma_f32_16x16x32_bf16 v[126:129], v[66:69], v[170:173], v[126:129]
	v_mfma_f32_16x16x32_bf16 v[122:125], v[74:77], v[170:173], v[122:125]
	v_mfma_f32_16x16x32_bf16 v[110:113], v[66:69], v[178:181], v[110:113]
	v_mfma_f32_16x16x32_bf16 v[106:109], v[74:77], v[178:181], v[106:109]
	v_mfma_f32_16x16x32_bf16 v[102:105], v[66:69], v[186:189], v[102:105]
	v_mfma_f32_16x16x32_bf16 v[98:101], v[74:77], v[186:189], v[98:101]
	v_mfma_f32_16x16x32_bf16 v[142:145], v[70:73], v[166:169], v[142:145]
	v_mfma_f32_16x16x32_bf16 v[138:141], v[78:81], v[166:169], v[138:141]
	v_mfma_f32_16x16x32_bf16 v[126:129], v[70:73], v[174:177], v[126:129]
	v_mfma_f32_16x16x32_bf16 v[122:125], v[78:81], v[174:177], v[122:125]
	v_mfma_f32_16x16x32_bf16 v[110:113], v[70:73], v[182:185], v[110:113]
	v_mfma_f32_16x16x32_bf16 v[106:109], v[78:81], v[182:185], v[106:109]
	v_mfma_f32_16x16x32_bf16 v[102:105], v[70:73], v[190:193], v[102:105]
	v_mfma_f32_16x16x32_bf16 v[98:101], v[78:81], v[190:193], v[98:101]
	s_setprio 0
	s_barrier
	s_add_i32 s39, 0, 0x14000
	v_add_u32_e32 v156, s39, v163
	s_add_i32 s28, s38, s60
	ds_read_b128 v[194:197], v156
	ds_read_b128 v[198:201], v156 offset:1024
	ds_read_b128 v[202:205], v156 offset:2048
	ds_read_b128 v[210:213], v156 offset:3072
	v_lshl_add_u64 v[156:157], s[52:53], 0, v[0:1]
	s_mov_b32 m0, s28
	v_lshl_add_u64 v[160:161], s[52:53], 0, v[146:147]
	global_load_lds_dwordx4 v[156:157], off
	s_add_i32 m0, s28, 0x2000
	s_nop 0
	global_load_lds_dwordx4 v[160:161], off
	s_barrier
	s_waitcnt lgkmcnt(0)
	s_setprio 1
	s_waitcnt lgkmcnt(0)
	v_mfma_f32_16x16x32_bf16 v[134:137], v[194:197], v[152:155], v[134:137]
	v_mfma_f32_16x16x32_bf16 v[130:133], v[202:205], v[152:155], v[130:133]
	v_mfma_f32_16x16x32_bf16 v[118:121], v[194:197], v[170:173], v[118:121]
	v_mfma_f32_16x16x32_bf16 v[114:117], v[202:205], v[170:173], v[114:117]
	v_mfma_f32_16x16x32_bf16 v[94:97], v[194:197], v[178:181], v[94:97]
	v_mfma_f32_16x16x32_bf16 v[90:93], v[202:205], v[178:181], v[90:93]
	v_mfma_f32_16x16x32_bf16 v[86:89], v[194:197], v[186:189], v[86:89]
	v_mfma_f32_16x16x32_bf16 v[82:85], v[202:205], v[186:189], v[82:85]
	v_mfma_f32_16x16x32_bf16 v[134:137], v[198:201], v[166:169], v[134:137]
	v_mfma_f32_16x16x32_bf16 v[130:133], v[210:213], v[166:169], v[130:133]
	v_mfma_f32_16x16x32_bf16 v[118:121], v[198:201], v[174:177], v[118:121]
	v_mfma_f32_16x16x32_bf16 v[114:117], v[210:213], v[174:177], v[114:117]
	v_mfma_f32_16x16x32_bf16 v[94:97], v[198:201], v[182:185], v[94:97]
	v_mfma_f32_16x16x32_bf16 v[90:93], v[210:213], v[182:185], v[90:93]
	v_mfma_f32_16x16x32_bf16 v[86:89], v[198:201], v[190:193], v[86:89]
	v_mfma_f32_16x16x32_bf16 v[82:85], v[210:213], v[190:193], v[82:85]
	s_setprio 0
	s_mov_b32 m0, s9
	v_lshl_add_u64 v[206:207], s[54:55], 0, v[0:1]
	s_barrier
	ds_read_b128 v[152:155], v165 offset:16384
	ds_read_b128 v[166:169], v165 offset:17408
	ds_read_b128 v[170:173], v165 offset:18432
	ds_read_b128 v[174:177], v165 offset:19456
	ds_read_b128 v[178:181], v165 offset:20480
	ds_read_b128 v[182:185], v165 offset:21504
	ds_read_b128 v[186:189], v165 offset:22528
	ds_read_b128 v[190:193], v165 offset:23552
	global_load_lds_dwordx4 v[206:207], off
	v_lshl_add_u64 v[214:215], s[54:55], 0, v[146:147]
	s_mov_b32 m0, s61
	s_nop 0
	global_load_lds_dwordx4 v[214:215], off
	s_barrier
	s_waitcnt lgkmcnt(0)
	s_setprio 1
	s_waitcnt lgkmcnt(0)
	v_mfma_f32_16x16x32_bf16 v[62:65], v[66:69], v[152:155], v[62:65]
	v_mfma_f32_16x16x32_bf16 v[58:61], v[74:77], v[152:155], v[58:61]
	v_mfma_f32_16x16x32_bf16 v[46:49], v[66:69], v[170:173], v[46:49]
	v_mfma_f32_16x16x32_bf16 v[42:45], v[74:77], v[170:173], v[42:45]
	v_mfma_f32_16x16x32_bf16 v[30:33], v[66:69], v[178:181], v[30:33]
	v_mfma_f32_16x16x32_bf16 v[26:29], v[74:77], v[178:181], v[26:29]
	v_mfma_f32_16x16x32_bf16 v[22:25], v[66:69], v[186:189], v[22:25]
	v_mfma_f32_16x16x32_bf16 v[14:17], v[74:77], v[186:189], v[14:17]
	v_mfma_f32_16x16x32_bf16 v[62:65], v[70:73], v[166:169], v[62:65]
	v_mfma_f32_16x16x32_bf16 v[58:61], v[78:81], v[166:169], v[58:61]
	v_mfma_f32_16x16x32_bf16 v[46:49], v[70:73], v[174:177], v[46:49]
	v_mfma_f32_16x16x32_bf16 v[42:45], v[78:81], v[174:177], v[42:45]
	v_mfma_f32_16x16x32_bf16 v[30:33], v[70:73], v[182:185], v[30:33]
	v_mfma_f32_16x16x32_bf16 v[26:29], v[78:81], v[182:185], v[26:29]
	v_mfma_f32_16x16x32_bf16 v[22:25], v[70:73], v[190:193], v[22:25]
	v_mfma_f32_16x16x32_bf16 v[14:17], v[78:81], v[190:193], v[14:17]
	s_setprio 0
	s_barrier
	s_add_u32 s28, s52, 0x200000
	s_addc_u32 s29, s53, 0
	s_add_i32 s38, s39, s60
	v_lshl_add_u64 v[66:67], s[28:29], 0, v[0:1]
	s_mov_b32 m0, s38
	s_nop 0
	global_load_lds_dwordx4 v[66:67], off
	v_lshl_add_u64 v[66:67], s[28:29], 0, v[146:147]
	s_add_i32 m0, s38, 0x2000
	s_nop 0
	global_load_lds_dwordx4 v[66:67], off
	s_waitcnt vmcnt(6)
	s_barrier
	s_setprio 1
	v_mfma_f32_16x16x32_bf16 v[54:57], v[194:197], v[152:155], v[54:57]
	v_mfma_f32_16x16x32_bf16 v[50:53], v[202:205], v[152:155], v[50:53]
	v_mfma_f32_16x16x32_bf16 v[38:41], v[194:197], v[170:173], v[38:41]
	v_mfma_f32_16x16x32_bf16 v[34:37], v[202:205], v[170:173], v[34:37]
	v_mfma_f32_16x16x32_bf16 v[18:21], v[194:197], v[178:181], v[18:21]
	v_mfma_f32_16x16x32_bf16 v[10:13], v[202:205], v[178:181], v[10:13]
	v_mfma_f32_16x16x32_bf16 v[6:9], v[194:197], v[186:189], v[6:9]
	v_mfma_f32_16x16x32_bf16 v[2:5], v[202:205], v[186:189], v[2:5]
	v_mfma_f32_16x16x32_bf16 v[54:57], v[198:201], v[166:169], v[54:57]
	v_mfma_f32_16x16x32_bf16 v[50:53], v[210:213], v[166:169], v[50:53]
	v_mfma_f32_16x16x32_bf16 v[38:41], v[198:201], v[174:177], v[38:41]
	v_mfma_f32_16x16x32_bf16 v[34:37], v[210:213], v[174:177], v[34:37]
	v_mfma_f32_16x16x32_bf16 v[18:21], v[198:201], v[182:185], v[18:21]
	v_mfma_f32_16x16x32_bf16 v[10:13], v[210:213], v[182:185], v[10:13]
	v_mfma_f32_16x16x32_bf16 v[6:9], v[198:201], v[190:193], v[6:9]
	v_mfma_f32_16x16x32_bf16 v[2:5], v[210:213], v[190:193], v[2:5]
	s_setprio 0
	s_add_i32 s38, 0, 0x18000
	v_add_u32_e32 v78, s38, v163
	s_barrier
	ds_read_b128 v[66:69], v78
	ds_read_b128 v[70:73], v78 offset:1024
	ds_read_b128 v[74:77], v78 offset:2048
	ds_read_b128 v[78:81], v78 offset:3072
	s_add_u32 s28, s54, 0x200000
	s_addc_u32 s29, s55, 0
	s_mov_b32 m0, s62
	v_lshl_add_u64 v[194:195], s[28:29], 0, v[0:1]
	ds_read_b128 v[152:155], v165 offset:32768
	ds_read_b128 v[166:169], v165 offset:33792
	ds_read_b128 v[170:173], v165 offset:34816
	ds_read_b128 v[174:177], v165 offset:35840
	ds_read_b128 v[178:181], v165 offset:36864
	ds_read_b128 v[182:185], v165 offset:37888
	ds_read_b128 v[186:189], v165 offset:38912
	ds_read_b128 v[190:193], v165 offset:39936
	global_load_lds_dwordx4 v[194:195], off
	v_lshl_add_u64 v[194:195], s[28:29], 0, v[146:147]
	s_mov_b32 m0, s63
	s_nop 0
	global_load_lds_dwordx4 v[194:195], off
	s_waitcnt lgkmcnt(8)
	s_barrier
	s_waitcnt lgkmcnt(0)
	s_setprio 1
	s_waitcnt lgkmcnt(0)
	v_mfma_f32_16x16x32_bf16 v[142:145], v[66:69], v[152:155], v[142:145]
	v_mfma_f32_16x16x32_bf16 v[138:141], v[74:77], v[152:155], v[138:141]
	v_mfma_f32_16x16x32_bf16 v[126:129], v[66:69], v[170:173], v[126:129]
	v_mfma_f32_16x16x32_bf16 v[122:125], v[74:77], v[170:173], v[122:125]
	v_mfma_f32_16x16x32_bf16 v[110:113], v[66:69], v[178:181], v[110:113]
	v_mfma_f32_16x16x32_bf16 v[106:109], v[74:77], v[178:181], v[106:109]
	v_mfma_f32_16x16x32_bf16 v[102:105], v[66:69], v[186:189], v[102:105]
	v_mfma_f32_16x16x32_bf16 v[98:101], v[74:77], v[186:189], v[98:101]
	v_mfma_f32_16x16x32_bf16 v[142:145], v[70:73], v[166:169], v[142:145]
	v_mfma_f32_16x16x32_bf16 v[138:141], v[78:81], v[166:169], v[138:141]
	v_mfma_f32_16x16x32_bf16 v[126:129], v[70:73], v[174:177], v[126:129]
	v_mfma_f32_16x16x32_bf16 v[122:125], v[78:81], v[174:177], v[122:125]
	v_mfma_f32_16x16x32_bf16 v[110:113], v[70:73], v[182:185], v[110:113]
	v_mfma_f32_16x16x32_bf16 v[106:109], v[78:81], v[182:185], v[106:109]
	v_mfma_f32_16x16x32_bf16 v[102:105], v[70:73], v[190:193], v[102:105]
	v_mfma_f32_16x16x32_bf16 v[98:101], v[78:81], v[190:193], v[98:101]
	s_setprio 0
	s_barrier
	s_add_i32 s39, 0, 0x1c000
	s_add_i32 s28, s38, s60
	v_add_u32_e32 v210, s39, v163
	v_lshl_add_u64 v[156:157], v[156:157], 0, s[36:37]
	s_mov_b32 m0, s28
	ds_read_b128 v[194:197], v210
	ds_read_b128 v[198:201], v210 offset:1024
	ds_read_b128 v[202:205], v210 offset:2048
	ds_read_b128 v[210:213], v210 offset:3072
	global_load_lds_dwordx4 v[156:157], off
	v_lshl_add_u64 v[156:157], v[160:161], 0, s[36:37]
	s_add_i32 m0, s28, 0x2000
	s_nop 0
	global_load_lds_dwordx4 v[156:157], off
	s_barrier
	s_waitcnt lgkmcnt(0)
	s_setprio 1
	s_waitcnt lgkmcnt(0)
	v_mfma_f32_16x16x32_bf16 v[134:137], v[194:197], v[152:155], v[134:137]
	v_mfma_f32_16x16x32_bf16 v[130:133], v[202:205], v[152:155], v[130:133]
	v_mfma_f32_16x16x32_bf16 v[118:121], v[194:197], v[170:173], v[118:121]
	v_mfma_f32_16x16x32_bf16 v[114:117], v[202:205], v[170:173], v[114:117]
	v_mfma_f32_16x16x32_bf16 v[94:97], v[194:197], v[178:181], v[94:97]
	v_mfma_f32_16x16x32_bf16 v[90:93], v[202:205], v[178:181], v[90:93]
	v_mfma_f32_16x16x32_bf16 v[86:89], v[194:197], v[186:189], v[86:89]
	v_mfma_f32_16x16x32_bf16 v[82:85], v[202:205], v[186:189], v[82:85]
	v_mfma_f32_16x16x32_bf16 v[134:137], v[198:201], v[166:169], v[134:137]
	v_mfma_f32_16x16x32_bf16 v[130:133], v[210:213], v[166:169], v[130:133]
	v_mfma_f32_16x16x32_bf16 v[118:121], v[198:201], v[174:177], v[118:121]
	v_mfma_f32_16x16x32_bf16 v[114:117], v[210:213], v[174:177], v[114:117]
	v_mfma_f32_16x16x32_bf16 v[94:97], v[198:201], v[182:185], v[94:97]
	v_mfma_f32_16x16x32_bf16 v[90:93], v[210:213], v[182:185], v[90:93]
	v_mfma_f32_16x16x32_bf16 v[86:89], v[198:201], v[190:193], v[86:89]
	v_mfma_f32_16x16x32_bf16 v[82:85], v[210:213], v[190:193], v[82:85]
	s_setprio 0
	s_mov_b32 m0, s66
	v_lshl_add_u64 v[156:157], v[206:207], 0, s[36:37]
	s_barrier
	ds_read_b128 v[152:155], v165 offset:49152
	ds_read_b128 v[166:169], v165 offset:50176
	ds_read_b128 v[170:173], v165 offset:51200
	ds_read_b128 v[174:177], v165 offset:52224
	ds_read_b128 v[178:181], v165 offset:53248
	ds_read_b128 v[182:185], v165 offset:54272
	ds_read_b128 v[186:189], v165 offset:55296
	ds_read_b128 v[190:193], v165 offset:56320
	global_load_lds_dwordx4 v[156:157], off
	v_lshl_add_u64 v[156:157], v[214:215], 0, s[36:37]
	s_mov_b32 m0, s67
	s_nop 0
	global_load_lds_dwordx4 v[156:157], off
	s_barrier
	s_waitcnt lgkmcnt(0)
	s_setprio 1
	s_waitcnt lgkmcnt(0)
	v_mfma_f32_16x16x32_bf16 v[62:65], v[66:69], v[152:155], v[62:65]
	v_mfma_f32_16x16x32_bf16 v[58:61], v[74:77], v[152:155], v[58:61]
	v_mfma_f32_16x16x32_bf16 v[46:49], v[66:69], v[170:173], v[46:49]
	v_mfma_f32_16x16x32_bf16 v[42:45], v[74:77], v[170:173], v[42:45]
	v_mfma_f32_16x16x32_bf16 v[30:33], v[66:69], v[178:181], v[30:33]
	v_mfma_f32_16x16x32_bf16 v[26:29], v[74:77], v[178:181], v[26:29]
	v_mfma_f32_16x16x32_bf16 v[22:25], v[66:69], v[186:189], v[22:25]
	v_mfma_f32_16x16x32_bf16 v[14:17], v[74:77], v[186:189], v[14:17]
	v_mfma_f32_16x16x32_bf16 v[62:65], v[70:73], v[166:169], v[62:65]
	v_mfma_f32_16x16x32_bf16 v[58:61], v[78:81], v[166:169], v[58:61]
	v_mfma_f32_16x16x32_bf16 v[46:49], v[70:73], v[174:177], v[46:49]
	v_mfma_f32_16x16x32_bf16 v[42:45], v[78:81], v[174:177], v[42:45]
	v_mfma_f32_16x16x32_bf16 v[30:33], v[70:73], v[182:185], v[30:33]
	v_mfma_f32_16x16x32_bf16 v[26:29], v[78:81], v[182:185], v[26:29]
	v_mfma_f32_16x16x32_bf16 v[22:25], v[70:73], v[190:193], v[22:25]
	v_mfma_f32_16x16x32_bf16 v[14:17], v[78:81], v[190:193], v[14:17]
	s_setprio 0
	s_barrier
	s_cmp_lt_i32 s75, 94
	s_cbranch_scc1 .Lpf_w2_skip
	s_lshl_b32 s100, s8, 21
	s_lshl_b32 s101, s70, 10
	s_add_i32 s100, s100, s101
	s_sub_i32 s101, s75, 94
	s_lshl_b32 s101, s101, 16
	s_add_i32 s100, s100, s101
	s_add_u32 s100, s44, s100
	s_addc_u32 s101, s45, 0
	v_lshrrev_b32_e32 v68, 5, v208
	v_lshlrev_b32_e32 v68, 13, v68
	v_bfe_u32 v69, v208, 2, 3
	v_lshl_or_b32 v68, v69, 7, v68
	v_and_b32_e32 v69, 3, v208
	v_lshl_or_b32 v68, v69, 2, v68
	s_mov_b32 m0, 0x20040
	s_nop 0
	global_load_lds_dword v68, s[100:101]
.Lpf_w2_skip:
	s_add_u32 s28, s52, 0x200080
	s_addc_u32 s29, s53, 0
	s_add_i32 s38, s39, s60
	v_lshl_add_u64 v[66:67], s[28:29], 0, v[0:1]
	s_mov_b32 m0, s38
	s_nop 0
	global_load_lds_dwordx4 v[66:67], off
	v_lshl_add_u64 v[66:67], s[28:29], 0, v[146:147]
	s_add_i32 m0, s38, 0x2000
	s_nop 0
	global_load_lds_dwordx4 v[66:67], off
	s_waitcnt vmcnt(6)
	s_barrier
	s_setprio 1
	v_mfma_f32_16x16x32_bf16 v[54:57], v[194:197], v[152:155], v[54:57]
	v_mfma_f32_16x16x32_bf16 v[50:53], v[202:205], v[152:155], v[50:53]
	v_mfma_f32_16x16x32_bf16 v[38:41], v[194:197], v[170:173], v[38:41]
	v_mfma_f32_16x16x32_bf16 v[34:37], v[202:205], v[170:173], v[34:37]
	v_mfma_f32_16x16x32_bf16 v[18:21], v[194:197], v[178:181], v[18:21]
	v_mfma_f32_16x16x32_bf16 v[10:13], v[202:205], v[178:181], v[10:13]
	v_mfma_f32_16x16x32_bf16 v[6:9], v[194:197], v[186:189], v[6:9]
	v_mfma_f32_16x16x32_bf16 v[2:5], v[202:205], v[186:189], v[2:5]
	v_mfma_f32_16x16x32_bf16 v[54:57], v[198:201], v[166:169], v[54:57]
	v_mfma_f32_16x16x32_bf16 v[50:53], v[210:213], v[166:169], v[50:53]
	v_mfma_f32_16x16x32_bf16 v[38:41], v[198:201], v[174:177], v[38:41]
	v_mfma_f32_16x16x32_bf16 v[34:37], v[210:213], v[174:177], v[34:37]
	v_mfma_f32_16x16x32_bf16 v[18:21], v[198:201], v[182:185], v[18:21]
	v_mfma_f32_16x16x32_bf16 v[10:13], v[210:213], v[182:185], v[10:13]
	v_mfma_f32_16x16x32_bf16 v[6:9], v[198:201], v[190:193], v[6:9]
	v_mfma_f32_16x16x32_bf16 v[2:5], v[210:213], v[190:193], v[2:5]
	s_setprio 0
	s_add_i32 s75, s75, 2
	s_add_u32 s73, s73, 0x100
	s_addc_u32 s74, s74, 0
	s_cmpk_gt_u32 s75, 0x7d
	s_mov_b64 s[28:29], s[50:51]
	s_barrier
	s_cbranch_scc0 .LBB0_44
	s_cmp_lt_i32 s8, 64
	s_cselect_b64 s[50:51], -1, 0
	s_cmp_gt_i32 s8, 63
	s_cbranch_scc0 .LBB0_35
	s_mov_b64 s[52:53], 0x18000
	s_mov_b64 s[28:29], s[46:47]
	s_branch .LBB0_36

.LBB0_99:
	s_add_u32 s56, s28, 0x100
	s_addc_u32 s57, s29, 0
	s_add_i32 s38, 0, 0x10000
	v_add_u32_e32 v110, s38, v169
	ds_read_b128 v[98:101], v110
	ds_read_b128 v[102:105], v110 offset:1024
	ds_read_b128 v[106:109], v110 offset:2048
	ds_read_b128 v[110:113], v110 offset:3072
	s_cmp_eq_u32 s81, 28
	s_cselect_b32 s61, s51, s57
	s_cselect_b32 s60, s77, s56
	s_cselect_b32 s59, s49, s80
	s_cselect_b32 s58, s78, s79
	v_lshl_add_u64 v[156:157], s[28:29], 0, v[150:151]
	s_add_i32 m0, s9, 0xc000
	ds_read_b128 v[152:155], v171
	ds_read_b128 v[160:163], v171 offset:1024
	ds_read_b128 v[164:167], v171 offset:2048
	ds_read_b128 v[172:175], v171 offset:3072
	ds_read_b128 v[176:179], v171 offset:4096
	ds_read_b128 v[180:183], v171 offset:5120
	ds_read_b128 v[184:187], v171 offset:6144
	ds_read_b128 v[188:191], v171 offset:7168
	global_load_lds_dwordx4 v[156:157], off
	v_lshl_add_u64 v[156:157], s[28:29], 0, v[148:149]
	s_add_i32 m0, s9, 0xe000
	s_nop 0
	global_load_lds_dwordx4 v[156:157], off
	s_waitcnt lgkmcnt(8)
	s_barrier
	s_waitcnt lgkmcnt(0)
	s_setprio 1
	s_waitcnt lgkmcnt(0)
	v_mfma_f32_16x16x32_bf16 v[142:145], v[98:101], v[152:155], v[142:145]
	v_mfma_f32_16x16x32_bf16 v[138:141], v[106:109], v[152:155], v[138:141]
	v_mfma_f32_16x16x32_bf16 v[126:129], v[98:101], v[164:167], v[126:129]
	v_mfma_f32_16x16x32_bf16 v[122:125], v[106:109], v[164:167], v[122:125]
	v_mfma_f32_16x16x32_bf16 v[94:97], v[98:101], v[176:179], v[94:97]
	v_mfma_f32_16x16x32_bf16 v[90:93], v[106:109], v[176:179], v[90:93]
	v_mfma_f32_16x16x32_bf16 v[86:89], v[98:101], v[184:187], v[86:89]
	v_mfma_f32_16x16x32_bf16 v[82:85], v[106:109], v[184:187], v[82:85]
	v_mfma_f32_16x16x32_bf16 v[142:145], v[102:105], v[160:163], v[142:145]
	v_mfma_f32_16x16x32_bf16 v[138:141], v[110:113], v[160:163], v[138:141]
	v_mfma_f32_16x16x32_bf16 v[126:129], v[102:105], v[172:175], v[126:129]
	v_mfma_f32_16x16x32_bf16 v[122:125], v[110:113], v[172:175], v[122:125]
	v_mfma_f32_16x16x32_bf16 v[94:97], v[102:105], v[180:183], v[94:97]
	v_mfma_f32_16x16x32_bf16 v[90:93], v[110:113], v[180:183], v[90:93]
	v_mfma_f32_16x16x32_bf16 v[86:89], v[102:105], v[188:191], v[86:89]
	v_mfma_f32_16x16x32_bf16 v[82:85], v[110:113], v[188:191], v[82:85]
	s_setprio 0
	s_barrier
	s_add_i32 s39, 0, 0x14000
	v_add_u32_e32 v156, s39, v169
	s_add_i32 s28, s38, s67
	ds_read_b128 v[192:195], v156
	ds_read_b128 v[196:199], v156 offset:1024
	ds_read_b128 v[200:203], v156 offset:2048
	ds_read_b128 v[204:207], v156 offset:3072
	v_lshl_add_u64 v[156:157], s[58:59], 0, v[0:1]
	s_mov_b32 m0, s28
	v_lshl_add_u64 v[210:211], s[58:59], 0, v[146:147]
	global_load_lds_dwordx4 v[156:157], off
	s_add_i32 m0, s28, 0x2000
	s_nop 0
	global_load_lds_dwordx4 v[210:211], off
	s_barrier
	s_waitcnt lgkmcnt(0)
	s_setprio 1
	s_waitcnt lgkmcnt(0)
	v_mfma_f32_16x16x32_bf16 v[134:137], v[192:195], v[152:155], v[134:137]
	v_mfma_f32_16x16x32_bf16 v[130:133], v[200:203], v[152:155], v[130:133]
	v_mfma_f32_16x16x32_bf16 v[118:121], v[192:195], v[164:167], v[118:121]
	v_mfma_f32_16x16x32_bf16 v[114:117], v[200:203], v[164:167], v[114:117]
	v_mfma_f32_16x16x32_bf16 v[78:81], v[192:195], v[176:179], v[78:81]
	v_mfma_f32_16x16x32_bf16 v[74:77], v[200:203], v[176:179], v[74:77]
	v_mfma_f32_16x16x32_bf16 v[70:73], v[192:195], v[184:187], v[70:73]
	v_mfma_f32_16x16x32_bf16 v[66:69], v[200:203], v[184:187], v[66:69]
	v_mfma_f32_16x16x32_bf16 v[134:137], v[196:199], v[160:163], v[134:137]
	v_mfma_f32_16x16x32_bf16 v[130:133], v[204:207], v[160:163], v[130:133]
	v_mfma_f32_16x16x32_bf16 v[118:121], v[196:199], v[172:175], v[118:121]
	v_mfma_f32_16x16x32_bf16 v[114:117], v[204:207], v[172:175], v[114:117]
	v_mfma_f32_16x16x32_bf16 v[78:81], v[196:199], v[180:183], v[78:81]
	v_mfma_f32_16x16x32_bf16 v[74:77], v[204:207], v[180:183], v[74:77]
	v_mfma_f32_16x16x32_bf16 v[70:73], v[196:199], v[188:191], v[70:73]
	v_mfma_f32_16x16x32_bf16 v[66:69], v[204:207], v[188:191], v[66:69]
	s_setprio 0
	s_mov_b32 m0, s9
	v_lshl_add_u64 v[212:213], s[60:61], 0, v[0:1]
	s_barrier
	ds_read_b128 v[152:155], v171 offset:16384
	ds_read_b128 v[160:163], v171 offset:17408
	ds_read_b128 v[164:167], v171 offset:18432
	ds_read_b128 v[172:175], v171 offset:19456
	ds_read_b128 v[176:179], v171 offset:20480
	ds_read_b128 v[180:183], v171 offset:21504
	ds_read_b128 v[184:187], v171 offset:22528
	ds_read_b128 v[188:191], v171 offset:23552
	global_load_lds_dwordx4 v[212:213], off
	v_lshl_add_u64 v[214:215], s[60:61], 0, v[146:147]
	s_mov_b32 m0, s68
	s_nop 0
	global_load_lds_dwordx4 v[214:215], off
	s_barrier
	s_waitcnt lgkmcnt(0)
	s_setprio 1
	s_waitcnt lgkmcnt(0)
	v_mfma_f32_16x16x32_bf16 v[62:65], v[98:101], v[152:155], v[62:65]
	v_mfma_f32_16x16x32_bf16 v[58:61], v[106:109], v[152:155], v[58:61]
	v_mfma_f32_16x16x32_bf16 v[46:49], v[98:101], v[164:167], v[46:49]
	v_mfma_f32_16x16x32_bf16 v[42:45], v[106:109], v[164:167], v[42:45]
	v_mfma_f32_16x16x32_bf16 v[30:33], v[98:101], v[176:179], v[30:33]
	v_mfma_f32_16x16x32_bf16 v[26:29], v[106:109], v[176:179], v[26:29]
	v_mfma_f32_16x16x32_bf16 v[22:25], v[98:101], v[184:187], v[22:25]
	v_mfma_f32_16x16x32_bf16 v[18:21], v[106:109], v[184:187], v[18:21]
	v_mfma_f32_16x16x32_bf16 v[62:65], v[102:105], v[160:163], v[62:65]
	v_mfma_f32_16x16x32_bf16 v[58:61], v[110:113], v[160:163], v[58:61]
	v_mfma_f32_16x16x32_bf16 v[46:49], v[102:105], v[172:175], v[46:49]
	v_mfma_f32_16x16x32_bf16 v[42:45], v[110:113], v[172:175], v[42:45]
	v_mfma_f32_16x16x32_bf16 v[30:33], v[102:105], v[180:183], v[30:33]
	v_mfma_f32_16x16x32_bf16 v[26:29], v[110:113], v[180:183], v[26:29]
	v_mfma_f32_16x16x32_bf16 v[22:25], v[102:105], v[188:191], v[22:25]
	v_mfma_f32_16x16x32_bf16 v[18:21], v[110:113], v[188:191], v[18:21]
	s_setprio 0
	s_barrier
	s_add_u32 s28, s58, 0x80000
	s_addc_u32 s29, s59, 0
	s_add_i32 s38, s39, s67
	v_lshl_add_u64 v[98:99], s[28:29], 0, v[0:1]
	s_mov_b32 m0, s38
	s_nop 0
	global_load_lds_dwordx4 v[98:99], off
	v_lshl_add_u64 v[98:99], s[28:29], 0, v[146:147]
	s_add_i32 m0, s38, 0x2000
	s_nop 0
	global_load_lds_dwordx4 v[98:99], off
	s_waitcnt vmcnt(6)
	s_barrier
	s_setprio 1
	v_mfma_f32_16x16x32_bf16 v[54:57], v[192:195], v[152:155], v[54:57]
	v_mfma_f32_16x16x32_bf16 v[50:53], v[200:203], v[152:155], v[50:53]
	v_mfma_f32_16x16x32_bf16 v[38:41], v[192:195], v[164:167], v[38:41]
	v_mfma_f32_16x16x32_bf16 v[34:37], v[200:203], v[164:167], v[34:37]
	v_mfma_f32_16x16x32_bf16 v[14:17], v[192:195], v[176:179], v[14:17]
	v_mfma_f32_16x16x32_bf16 v[10:13], v[200:203], v[176:179], v[10:13]
	v_mfma_f32_16x16x32_bf16 v[6:9], v[192:195], v[184:187], v[6:9]
	v_mfma_f32_16x16x32_bf16 v[2:5], v[200:203], v[184:187], v[2:5]
	v_mfma_f32_16x16x32_bf16 v[54:57], v[196:199], v[160:163], v[54:57]
	v_mfma_f32_16x16x32_bf16 v[50:53], v[204:207], v[160:163], v[50:53]
	v_mfma_f32_16x16x32_bf16 v[38:41], v[196:199], v[172:175], v[38:41]
	v_mfma_f32_16x16x32_bf16 v[34:37], v[204:207], v[172:175], v[34:37]
	v_mfma_f32_16x16x32_bf16 v[14:17], v[196:199], v[180:183], v[14:17]
	v_mfma_f32_16x16x32_bf16 v[10:13], v[204:207], v[180:183], v[10:13]
	v_mfma_f32_16x16x32_bf16 v[6:9], v[196:199], v[188:191], v[6:9]
	v_mfma_f32_16x16x32_bf16 v[2:5], v[204:207], v[188:191], v[2:5]
	s_setprio 0
	s_add_i32 s38, 0, 0x18000
	v_add_u32_e32 v110, s38, v169
	s_barrier
	ds_read_b128 v[98:101], v110
	ds_read_b128 v[102:105], v110 offset:1024
	ds_read_b128 v[106:109], v110 offset:2048
	ds_read_b128 v[110:113], v110 offset:3072
	s_add_u32 s28, s60, 0x80000
	s_addc_u32 s29, s61, 0
	s_mov_b32 m0, s69
	v_lshl_add_u64 v[192:193], s[28:29], 0, v[0:1]
	ds_read_b128 v[152:155], v171 offset:32768
	ds_read_b128 v[160:163], v171 offset:33792
	ds_read_b128 v[164:167], v171 offset:34816
	ds_read_b128 v[172:175], v171 offset:35840
	ds_read_b128 v[176:179], v171 offset:36864
	ds_read_b128 v[180:183], v171 offset:37888
	ds_read_b128 v[184:187], v171 offset:38912
	ds_read_b128 v[188:191], v171 offset:39936
	global_load_lds_dwordx4 v[192:193], off
	v_lshl_add_u64 v[192:193], s[28:29], 0, v[146:147]
	s_mov_b32 m0, s70
	s_nop 0
	global_load_lds_dwordx4 v[192:193], off
	s_waitcnt lgkmcnt(8)
	s_barrier
	s_waitcnt lgkmcnt(0)
	s_setprio 1
	s_waitcnt lgkmcnt(0)
	v_mfma_f32_16x16x32_bf16 v[142:145], v[98:101], v[152:155], v[142:145]
	v_mfma_f32_16x16x32_bf16 v[138:141], v[106:109], v[152:155], v[138:141]
	v_mfma_f32_16x16x32_bf16 v[126:129], v[98:101], v[164:167], v[126:129]
	v_mfma_f32_16x16x32_bf16 v[122:125], v[106:109], v[164:167], v[122:125]
	v_mfma_f32_16x16x32_bf16 v[94:97], v[98:101], v[176:179], v[94:97]
	v_mfma_f32_16x16x32_bf16 v[90:93], v[106:109], v[176:179], v[90:93]
	v_mfma_f32_16x16x32_bf16 v[86:89], v[98:101], v[184:187], v[86:89]
	v_mfma_f32_16x16x32_bf16 v[82:85], v[106:109], v[184:187], v[82:85]
	v_mfma_f32_16x16x32_bf16 v[142:145], v[102:105], v[160:163], v[142:145]
	v_mfma_f32_16x16x32_bf16 v[138:141], v[110:113], v[160:163], v[138:141]
	v_mfma_f32_16x16x32_bf16 v[126:129], v[102:105], v[172:175], v[126:129]
	v_mfma_f32_16x16x32_bf16 v[122:125], v[110:113], v[172:175], v[122:125]
	v_mfma_f32_16x16x32_bf16 v[94:97], v[102:105], v[180:183], v[94:97]
	v_mfma_f32_16x16x32_bf16 v[90:93], v[110:113], v[180:183], v[90:93]
	v_mfma_f32_16x16x32_bf16 v[86:89], v[102:105], v[188:191], v[86:89]
	v_mfma_f32_16x16x32_bf16 v[82:85], v[110:113], v[188:191], v[82:85]
	s_setprio 0
	s_barrier
	s_add_i32 s39, 0, 0x1c000
	s_add_i32 s28, s38, s67
	v_add_u32_e32 v204, s39, v169
	v_lshl_add_u64 v[156:157], v[156:157], 0, s[36:37]
	s_mov_b32 m0, s28
	ds_read_b128 v[192:195], v204
	ds_read_b128 v[196:199], v204 offset:1024
	ds_read_b128 v[200:203], v204 offset:2048
	ds_read_b128 v[204:207], v204 offset:3072
	global_load_lds_dwordx4 v[156:157], off
	v_lshl_add_u64 v[156:157], v[210:211], 0, s[36:37]
	s_add_i32 m0, s28, 0x2000
	s_nop 0
	global_load_lds_dwordx4 v[156:157], off
	s_barrier
	s_waitcnt lgkmcnt(0)
	s_setprio 1
	s_waitcnt lgkmcnt(0)
	v_mfma_f32_16x16x32_bf16 v[134:137], v[192:195], v[152:155], v[134:137]
	v_mfma_f32_16x16x32_bf16 v[130:133], v[200:203], v[152:155], v[130:133]
	v_mfma_f32_16x16x32_bf16 v[118:121], v[192:195], v[164:167], v[118:121]
	v_mfma_f32_16x16x32_bf16 v[114:117], v[200:203], v[164:167], v[114:117]
	v_mfma_f32_16x16x32_bf16 v[78:81], v[192:195], v[176:179], v[78:81]
	v_mfma_f32_16x16x32_bf16 v[74:77], v[200:203], v[176:179], v[74:77]
	v_mfma_f32_16x16x32_bf16 v[70:73], v[192:195], v[184:187], v[70:73]
	v_mfma_f32_16x16x32_bf16 v[66:69], v[200:203], v[184:187], v[66:69]
	v_mfma_f32_16x16x32_bf16 v[134:137], v[196:199], v[160:163], v[134:137]
	v_mfma_f32_16x16x32_bf16 v[130:133], v[204:207], v[160:163], v[130:133]
	v_mfma_f32_16x16x32_bf16 v[118:121], v[196:199], v[172:175], v[118:121]
	v_mfma_f32_16x16x32_bf16 v[114:117], v[204:207], v[172:175], v[114:117]
	v_mfma_f32_16x16x32_bf16 v[78:81], v[196:199], v[180:183], v[78:81]
	v_mfma_f32_16x16x32_bf16 v[74:77], v[204:207], v[180:183], v[74:77]
	v_mfma_f32_16x16x32_bf16 v[70:73], v[196:199], v[188:191], v[70:73]
	v_mfma_f32_16x16x32_bf16 v[66:69], v[204:207], v[188:191], v[66:69]
	s_setprio 0
	s_mov_b32 m0, s72
	v_lshl_add_u64 v[156:157], v[212:213], 0, s[36:37]
	s_barrier
	ds_read_b128 v[152:155], v171 offset:49152
	ds_read_b128 v[160:163], v171 offset:50176
	ds_read_b128 v[164:167], v171 offset:51200
	ds_read_b128 v[172:175], v171 offset:52224
	ds_read_b128 v[176:179], v171 offset:53248
	ds_read_b128 v[180:183], v171 offset:54272
	ds_read_b128 v[184:187], v171 offset:55296
	ds_read_b128 v[188:191], v171 offset:56320
	global_load_lds_dwordx4 v[156:157], off
	v_lshl_add_u64 v[156:157], v[214:215], 0, s[36:37]
	s_mov_b32 m0, s73
	s_nop 0
	global_load_lds_dwordx4 v[156:157], off
	s_barrier
	s_waitcnt lgkmcnt(0)
	s_setprio 1
	s_waitcnt lgkmcnt(0)
	v_mfma_f32_16x16x32_bf16 v[62:65], v[98:101], v[152:155], v[62:65]
	v_mfma_f32_16x16x32_bf16 v[58:61], v[106:109], v[152:155], v[58:61]
	v_mfma_f32_16x16x32_bf16 v[46:49], v[98:101], v[164:167], v[46:49]
	v_mfma_f32_16x16x32_bf16 v[42:45], v[106:109], v[164:167], v[42:45]
	v_mfma_f32_16x16x32_bf16 v[30:33], v[98:101], v[176:179], v[30:33]
	v_mfma_f32_16x16x32_bf16 v[26:29], v[106:109], v[176:179], v[26:29]
	v_mfma_f32_16x16x32_bf16 v[22:25], v[98:101], v[184:187], v[22:25]
	v_mfma_f32_16x16x32_bf16 v[18:21], v[106:109], v[184:187], v[18:21]
	v_mfma_f32_16x16x32_bf16 v[62:65], v[102:105], v[160:163], v[62:65]
	v_mfma_f32_16x16x32_bf16 v[58:61], v[110:113], v[160:163], v[58:61]
	v_mfma_f32_16x16x32_bf16 v[46:49], v[102:105], v[172:175], v[46:49]
	v_mfma_f32_16x16x32_bf16 v[42:45], v[110:113], v[172:175], v[42:45]
	v_mfma_f32_16x16x32_bf16 v[30:33], v[102:105], v[180:183], v[30:33]
	v_mfma_f32_16x16x32_bf16 v[26:29], v[110:113], v[180:183], v[26:29]
	v_mfma_f32_16x16x32_bf16 v[22:25], v[102:105], v[188:191], v[22:25]
	v_mfma_f32_16x16x32_bf16 v[18:21], v[110:113], v[188:191], v[18:21]
	s_setprio 0
	s_barrier
	s_lshl_b32 s100, s8, 21
	s_lshl_b32 s101, s76, 10
	s_add_i32 s100, s100, s101
	s_sub_i32 s101, s81, -2
	s_lshl_b32 s101, s101, 16
	s_add_i32 s100, s100, s101
	s_add_u32 s100, s26, s100
	s_addc_u32 s101, s27, 0
	v_lshrrev_b32_e32 v100, 5, v208
	v_lshlrev_b32_e32 v100, 13, v100
	v_bfe_u32 v101, v208, 2, 3
	v_lshl_or_b32 v100, v101, 7, v100
	v_and_b32_e32 v101, 3, v208
	v_lshl_or_b32 v100, v101, 2, v100
	s_mov_b32 m0, 0x20040
	s_nop 0
	global_load_lds_dword v100, s[100:101]
	s_add_u32 s28, s58, 0x80080
	s_addc_u32 s29, s59, 0
	s_add_i32 s38, s39, s67
	v_lshl_add_u64 v[98:99], s[28:29], 0, v[0:1]
	s_mov_b32 m0, s38
	s_nop 0
	global_load_lds_dwordx4 v[98:99], off
	v_lshl_add_u64 v[98:99], s[28:29], 0, v[146:147]
	s_add_i32 m0, s38, 0x2000
	s_nop 0
	global_load_lds_dwordx4 v[98:99], off
	s_waitcnt vmcnt(6)
	s_barrier
	s_setprio 1
	v_mfma_f32_16x16x32_bf16 v[54:57], v[192:195], v[152:155], v[54:57]
	v_mfma_f32_16x16x32_bf16 v[50:53], v[200:203], v[152:155], v[50:53]
	v_mfma_f32_16x16x32_bf16 v[38:41], v[192:195], v[164:167], v[38:41]
	v_mfma_f32_16x16x32_bf16 v[34:37], v[200:203], v[164:167], v[34:37]
	v_mfma_f32_16x16x32_bf16 v[14:17], v[192:195], v[176:179], v[14:17]
	v_mfma_f32_16x16x32_bf16 v[10:13], v[200:203], v[176:179], v[10:13]
	v_mfma_f32_16x16x32_bf16 v[6:9], v[192:195], v[184:187], v[6:9]
	v_mfma_f32_16x16x32_bf16 v[2:5], v[200:203], v[184:187], v[2:5]
	v_mfma_f32_16x16x32_bf16 v[54:57], v[196:199], v[160:163], v[54:57]
	v_mfma_f32_16x16x32_bf16 v[50:53], v[204:207], v[160:163], v[50:53]
	v_mfma_f32_16x16x32_bf16 v[38:41], v[196:199], v[172:175], v[38:41]
	v_mfma_f32_16x16x32_bf16 v[34:37], v[204:207], v[172:175], v[34:37]
	v_mfma_f32_16x16x32_bf16 v[14:17], v[196:199], v[180:183], v[14:17]
	v_mfma_f32_16x16x32_bf16 v[10:13], v[204:207], v[180:183], v[10:13]
	v_mfma_f32_16x16x32_bf16 v[6:9], v[196:199], v[188:191], v[6:9]
	v_mfma_f32_16x16x32_bf16 v[2:5], v[204:207], v[188:191], v[2:5]
	s_setprio 0
	s_add_i32 s81, s81, 2
	s_add_u32 s79, s79, 0x100
	s_addc_u32 s80, s80, 0
	s_cmp_gt_u32 s81, 29
	s_mov_b64 s[28:29], s[56:57]
	s_barrier
	s_cbranch_scc0 .LBB0_99
	s_cmp_lt_i32 s8, 64
	s_cselect_b64 s[58:59], -1, 0
	s_cmp_gt_i32 s8, 63
	s_cbranch_scc0 .LBB0_90
	s_mov_b64 s[60:61], 0x18000
	s_mov_b64 s[28:29], s[46:47]
	s_mov_b64 s[56:57], s[24:25]
	s_branch .LBB0_91

	.amdhsa_kernel _Z4mega6Paramsii
		.amdhsa_group_segment_fixed_size 512
		.amdhsa_private_segment_fixed_size 0
		.amdhsa_kernarg_size 512
		.amdhsa_user_sgpr_count 2
		.amdhsa_user_sgpr_dispatch_ptr 0
		.amdhsa_user_sgpr_queue_ptr 0
		.amdhsa_user_sgpr_kernarg_segment_ptr 1
		.amdhsa_user_sgpr_dispatch_id 0
		.amdhsa_user_sgpr_kernarg_preload_length 0
		.amdhsa_user_sgpr_kernarg_preload_offset 0
		.amdhsa_user_sgpr_private_segment_size 0
		.amdhsa_uses_dynamic_stack 0
		.amdhsa_enable_private_segment 0
		.amdhsa_system_sgpr_workgroup_id_x 1
		.amdhsa_system_sgpr_workgroup_id_y 0
		.amdhsa_system_sgpr_workgroup_id_z 0
		.amdhsa_system_sgpr_workgroup_info 0
		.amdhsa_system_vgpr_workitem_id 2
		.amdhsa_next_free_vgpr 256
		.amdhsa_next_free_sgpr 102
		.amdhsa_accum_offset 256
		.amdhsa_reserve_vcc 1
		.amdhsa_float_round_mode_32 0
		.amdhsa_float_round_mode_16_64 0
		.amdhsa_float_denorm_mode_32 3
		.amdhsa_float_denorm_mode_16_64 3
		.amdhsa_dx10_clamp 1
		.amdhsa_ieee_mode 1
		.amdhsa_fp16_overflow 0
		.amdhsa_tg_split 0
		.amdhsa_exception_fp_ieee_invalid_op 0
		.amdhsa_exception_fp_denorm_src 0
		.amdhsa_exception_fp_ieee_div_zero 0
		.amdhsa_exception_fp_ieee_overflow 0
		.amdhsa_exception_fp_ieee_underflow 0
		.amdhsa_exception_fp_ieee_inexact 0
		.amdhsa_exception_int_div_zero 0
	.end_amdhsa_kernel

amdhsa.kernels:
  - .agpr_count:     0
    .args:
      - .offset:         0
        .size:           248
        .value_kind:     by_value
      - .offset:         248
        .size:           4
        .value_kind:     by_value
      - .offset:         252
        .size:           4
        .value_kind:     by_value
      - .offset:         256
        .size:           4
        .value_kind:     hidden_block_count_x
      - .offset:         260
        .size:           4
        .value_kind:     hidden_block_count_y
      - .offset:         264
        .size:           4
        .value_kind:     hidden_block_count_z
      - .offset:         268
        .size:           2
        .value_kind:     hidden_group_size_x
      - .offset:         270
        .size:           2
        .value_kind:     hidden_group_size_y
      - .offset:         272
        .size:           2
        .value_kind:     hidden_group_size_z
      - .offset:         274
        .size:           2
        .value_kind:     hidden_remainder_x
      - .offset:         276
        .size:           2
        .value_kind:     hidden_remainder_y
      - .offset:         278
        .size:           2
        .value_kind:     hidden_remainder_z
      - .offset:         296
        .size:           8
        .value_kind:     hidden_global_offset_x
      - .offset:         304
        .size:           8
        .value_kind:     hidden_global_offset_y
      - .offset:         312
        .size:           8
        .value_kind:     hidden_global_offset_z
      - .offset:         320
        .size:           2
        .value_kind:     hidden_grid_dims
      - .offset:         344
        .size:           8
        .value_kind:     hidden_multigrid_sync_arg
      - .offset:         376
        .size:           4
        .value_kind:     hidden_dynamic_lds_size
    .group_segment_fixed_size: 512
    .kernarg_segment_align: 8
    .kernarg_segment_size: 512
    .language:       OpenCL C
    .language_version:
      - 2
      - 0
    .max_flat_workgroup_size: 512
    .name:           _Z4mega6Paramsii
    .private_segment_fixed_size: 0
    .sgpr_count:     108
    .sgpr_spill_count: 76
    .symbol:         _Z4mega6Paramsii.kd
    .uniform_work_group_size: 1
    .uses_dynamic_stack: false
    .vgpr_count:     256
    .vgpr_spill_count: 0
    .wavefront_size: 64
